# P0: fourth weight-conversion tile moved from the first 192 conversion waves to the x-row waves
# baseline (speedup 1.0000x reference)
.LBB0_106:
	v_writelane_b32 v239, s23, 6
	s_or_b64 exec, exec, s[12:13]
	s_movk_i32 s0, 0x23f
	v_cmp_lt_i32_e32 vcc, s0, v62
	v_readlane_b32 s0, v239, 2
	v_readlane_b32 s1, v239, 3
	s_movk_i32 s16, 0xc0
	v_cmp_gt_i32_e64 s[14:15], s16, v62
	s_cmp_eq_u32 s0, 0x100
	s_cselect_b64 s[16:17], -1, 0
	s_and_b64 s[14:15], s[14:15], s[16:17]
	s_cmpk_lt_i32 s0, 0x49
	s_cselect_b64 s[0:1], -1, 0
	s_or_b64 s[0:1], s[0:1], vcc
	s_or_b64 s[0:1], s[0:1], s[14:15]
	s_and_saveexec_b64 s[6:7], s[0:1]
	s_cbranch_execz .LBB0_116
	v_readlane_b32 s0, v239, 2
	s_cmpk_gt_i32 s0, 0x48
	v_add_u32_e32 v0, 0xfffffdc0, v62
	s_cselect_b64 vcc, -1, 0
	v_readlane_b32 s1, v239, 3
	v_cndmask_b32_e32 v69, v62, v0, vcc
	v_add_u32_e32 v0, 0x1140, v62
	v_cndmask_b32_e64 v69, v69, v0, s[14:15]
	s_movk_i32 s0, 0x1200
	v_cmp_gt_i32_e64 s[0:1], s0, v69
	s_and_b64 exec, exec, s[0:1]
	s_cbranch_execz .LBB0_116
	v_readlane_b32 s12, v239, 6
	s_movk_i32 s42, 0x11ff
	s_cmp_lg_u64 s[16:17], 0
	s_cselect_b32 s42, 0x113f, s42
	s_add_i32 s3, s12, 0xfffffdc0
	s_and_b64 s[0:1], vcc, exec
	s_cselect_b32 s3, s3, s12
	s_add_u32 s0, s30, 0x13200000
	s_addc_u32 s1, s31, 0
	s_add_u32 s12, s30, 0xce00000
	s_addc_u32 s13, s31, 0
	s_cmp_lg_u64 s[80:81], 0
	v_or_b32_e32 v70, 0xffffe400, v68
	s_mov_b64 s[14:15], 0
	s_cselect_b64 s[16:17], -1, 0
	v_lshlrev_b32_e32 v71, 6, v69
	s_lshl_b32 s20, s3, 6
	v_lshlrev_b32_e32 v72, 1, v69
	s_lshl_b32 s21, s3, 1
	s_movk_i32 s22, 0xdff
	v_mov_b32_e32 v1, 0
	s_mov_b32 s23, 0xe000
	s_mov_b32 s24, 0x1c000
	s_mov_b32 s25, 0x2a000
	s_mov_b32 s26, 0x38000
	s_mov_b32 s27, 0x46000
	s_mov_b32 s36, 0x54000
	s_mov_b32 s37, 0x62000
	s_mov_b32 s38, 0x70000
	s_mov_b32 s39, 0x7e000
	s_movk_i32 s40, 0xffc0
	s_movk_i32 s41, 0x1000
	s_branch .LBB0_111
